# run-time XCD census (HW_REG_XCC_ID): when every blockIdx%8 group sits on one XCD the 15 batch-local seams skip buffer_wbl2 sc1 (acquire kept); otherwise original seams
# speedup vs baseline: 1.0112x; 1.0112x over previous
.LBB0_135:
	s_getreg_b32 s98, hwreg(HW_REG_XCC_ID, 0, 4)
	s_lshl_b32 s98, 1, s98
	v_readlane_b32 s99, v251, 2
	v_readlane_b32 s100, v251, 18
	v_readlane_b32 s101, v251, 19
	s_nop 4
	s_and_b32 s99, s99, 7
	s_lshl_b32 s99, s99, 8
	s_add_u32 s99, s99, 0x3880
	v_mov_b32_e32 v228, s99
	v_mov_b32_e32 v229, s98
	s_mov_b64 vcc, exec
	s_mov_b64 exec, 1
	global_atomic_or v228, v229, s[100:101] sc1
	s_mov_b64 exec, vcc
	v_lshl_or_b32 v0, s66, 6, v94
	s_movk_i32 s0, 0x400
	v_cmp_gt_i32_e32 vcc, s0, v0
	s_and_saveexec_b64 s[0:1], vcc
	v_readlane_b32 s44, v251, 55
	v_readlane_b32 s45, v251, 56
	s_cbranch_execz .LBB0_145
	v_and_b32_e32 v1, 15, v53
	v_cmp_ne_u32_e32 vcc, 0, v1
	v_mov_b64_e32 v[12:13], 1.0
	s_and_saveexec_b64 s[4:5], vcc
	s_cbranch_execz .LBB0_140
	s_mov_b32 s8, 0x3c1c381e
	s_mov_b64 s[6:7], 0
	v_mov_b64_e32 v[12:13], 1.0
	s_mov_b32 s9, 0x3fe1feb3

.LBB0_203:
	v_readlane_b32 s98, v251, 18
	v_readlane_b32 s99, v251, 19
	s_nop 4
	v_mov_b32_e32 v228, 0x3880
	global_load_dword v229, v228, s[98:99] offset:0 sc1
	global_load_dword v230, v228, s[98:99] offset:256 sc1
	global_load_dword v231, v228, s[98:99] offset:512 sc1
	global_load_dword v232, v228, s[98:99] offset:768 sc1
	global_load_dword v233, v228, s[98:99] offset:1024 sc1
	global_load_dword v234, v228, s[98:99] offset:1280 sc1
	global_load_dword v235, v228, s[98:99] offset:1536 sc1
	global_load_dword v236, v228, s[98:99] offset:1792 sc1
	s_waitcnt vmcnt(0)
	s_mov_b32 s100, 1
	v_readfirstlane_b32 s101, v229
	s_nop 1
	s_bcnt1_i32_b32 s101, s101
	s_cmp_eq_u32 s101, 1
	s_cselect_b32 s100, s100, 0
	v_readfirstlane_b32 s101, v230
	s_nop 1
	s_bcnt1_i32_b32 s101, s101
	s_cmp_eq_u32 s101, 1
	s_cselect_b32 s100, s100, 0
	v_readfirstlane_b32 s101, v231
	s_nop 1
	s_bcnt1_i32_b32 s101, s101
	s_cmp_eq_u32 s101, 1
	s_cselect_b32 s100, s100, 0
	v_readfirstlane_b32 s101, v232
	s_nop 1
	s_bcnt1_i32_b32 s101, s101
	s_cmp_eq_u32 s101, 1
	s_cselect_b32 s100, s100, 0
	v_readfirstlane_b32 s101, v233
	s_nop 1
	s_bcnt1_i32_b32 s101, s101
	s_cmp_eq_u32 s101, 1
	s_cselect_b32 s100, s100, 0
	v_readfirstlane_b32 s101, v234
	s_nop 1
	s_bcnt1_i32_b32 s101, s101
	s_cmp_eq_u32 s101, 1
	s_cselect_b32 s100, s100, 0
	v_readfirstlane_b32 s101, v235
	s_nop 1
	s_bcnt1_i32_b32 s101, s101
	s_cmp_eq_u32 s101, 1
	s_cselect_b32 s100, s100, 0
	v_readfirstlane_b32 s101, v236
	s_nop 1
	s_bcnt1_i32_b32 s101, s101
	s_cmp_eq_u32 s101, 1
	s_cselect_b32 s100, s100, 0
	v_writelane_b32 v255, s100, 8
	v_writelane_b32 v251, s90, 57
	v_mov_b32_e32 v189, 0
	v_mbcnt_hi_u32_b32 v207, -1, v51
	v_writelane_b32 v251, s91, 58
	v_writelane_b32 v251, s88, 59
	v_mov_b32_e32 v209, 0x358637bd
	v_mov_b32_e32 v250, 1
	v_writelane_b32 v251, s89, 60
	v_writelane_b32 v251, s66, 61
	v_mov_b32_e32 v213, 0xff800000
	v_mov_b64_e32 v[190:191], 0x200
	v_writelane_b32 v251, s67, 62
	v_mov_b64_e32 v[192:193], 0x1ff
	v_readlane_b32 s48, v251, 4
	v_readlane_b32 s60, v251, 16
	v_readlane_b32 s61, v251, 17
	v_readlane_b32 s62, v251, 18
	v_readlane_b32 s63, v251, 19
	s_mov_b64 s[24:25], s[60:61]
	s_mov_b64 s[26:27], s[62:63]
	s_add_u32 s0, s26, 0x4000000
	v_readlane_b32 s49, v251, 5
	v_readlane_b32 s50, v251, 6
	v_readlane_b32 s51, v251, 7
	v_readlane_b32 s52, v251, 8
	v_readlane_b32 s53, v251, 9
	v_readlane_b32 s54, v251, 10
	v_readlane_b32 s55, v251, 11
	v_readlane_b32 s56, v251, 12
	v_readlane_b32 s57, v251, 13
	v_readlane_b32 s58, v251, 14
	v_readlane_b32 s59, v251, 15
	v_writelane_b32 v251, s0, 63
	s_addc_u32 s0, s27, 0
	s_add_u32 s90, s26, 0x10000000
	s_addc_u32 s91, s27, 0
	s_add_u32 s92, s26, 0x1c000000
	s_addc_u32 s93, s27, 0
	v_writelane_b32 v252, s0, 0
	s_add_u32 s0, s26, 0x101000
	s_addc_u32 s1, s27, 0
	v_writelane_b32 v252, s0, 1
	v_readlane_b32 s18, v251, 2
	v_readlane_b32 s20, v251, 3
	v_writelane_b32 v252, s1, 2
	s_add_u32 s0, s26, 0x2e00000
	v_writelane_b32 v252, s0, 3
	s_addc_u32 s0, s27, 0
	v_writelane_b32 v252, s0, 4
	s_and_b32 s0, s18, 1
	s_add_u32 s22, s26, 0x1d000000
	s_addc_u32 s23, s27, 0
	s_cmpk_lt_i32 s18, 0x500
	v_writelane_b32 v252, s0, 5
	s_cselect_b64 s[0:1], -1, 0
	v_writelane_b32 v252, s0, 6
	s_ashr_i32 s2, s18, 31
	s_ashr_i32 s33, s3, 31
	v_writelane_b32 v252, s1, 7
	s_lshr_b32 s0, s2, 29
	s_add_i32 s0, s18, s0
	s_ashr_i32 s8, s0, 3
	s_and_b32 s0, s0, -8
	s_sub_i32 s9, s18, s0
	s_cmpk_lt_i32 s18, 0x600
	s_cselect_b64 s[0:1], -1, 0
	s_cmpk_lt_i32 s18, 0x200
	v_writelane_b32 v252, s0, 8
	s_cselect_b64 s[28:29], -1, 0
	s_lshl_b32 s10, s9, 6
	v_writelane_b32 v252, s1, 9
	s_add_u32 s0, s26, 0x200
	s_addc_u32 s1, s27, 0
	v_writelane_b32 v252, s0, 10
	v_mov_b64_e32 v[248:249], 0x500
	v_mov_b64_e32 v[210:211], 0x4ff
	v_writelane_b32 v252, s1, 11
	s_add_u32 s0, s26, 0x1000
	s_addc_u32 s1, s27, 0
	v_writelane_b32 v252, s0, 12
	v_mov_b32_e32 v212, 0x3e38aa3b
	v_mov_b64_e32 v[198:199], 0x600
	v_writelane_b32 v252, s1, 13
	s_add_u32 s0, s26, 0x1100
	s_addc_u32 s1, s27, 0
	v_writelane_b32 v252, s0, 14
	v_mov_b64_e32 v[200:201], 0x5ff
	v_mov_b32_e32 v214, 0x21c00
	v_writelane_b32 v252, s1, 15
	s_add_u32 s0, s26, 0x1200
	s_addc_u32 s1, s27, 0
	v_writelane_b32 v252, s0, 16
	s_mov_b64 s[62:63], 0x80
	s_mov_b64 s[88:89], 0x8000
	v_writelane_b32 v252, s1, 17
	s_add_u32 s0, s26, 0x1300
	s_addc_u32 s1, s27, 0
	v_writelane_b32 v252, s0, 18
	s_cmp_eq_u32 s94, 15
	s_nop 0
	v_writelane_b32 v252, s1, 19
	s_cselect_b64 s[0:1], -1, 0
	v_writelane_b32 v252, s0, 20
	s_cmp_eq_u32 s94, 14
	s_nop 0
	v_writelane_b32 v252, s1, 21
	s_cselect_b64 s[0:1], -1, 0
	v_writelane_b32 v252, s0, 22
	s_cmp_eq_u32 s94, 13
	s_nop 0
	v_writelane_b32 v252, s1, 23
	s_cselect_b64 s[0:1], -1, 0
	v_writelane_b32 v252, s0, 24
	s_cmp_eq_u32 s94, 12
	s_nop 0
	v_writelane_b32 v252, s1, 25
	s_cselect_b64 s[0:1], -1, 0
	v_writelane_b32 v252, s0, 26
	s_cmp_eq_u32 s94, 11
	s_nop 0
	v_writelane_b32 v252, s1, 27
	s_cselect_b64 s[0:1], -1, 0
	v_writelane_b32 v252, s0, 28
	s_cmp_eq_u32 s94, 10
	s_nop 0
	v_writelane_b32 v252, s1, 29
	s_cselect_b64 s[0:1], -1, 0
	v_writelane_b32 v252, s0, 30
	s_cmp_eq_u32 s94, 9
	s_nop 0
	v_writelane_b32 v252, s1, 31
	s_cselect_b64 s[0:1], -1, 0
	v_writelane_b32 v252, s0, 32
	s_cmp_eq_u32 s94, 8
	s_nop 0
	v_writelane_b32 v252, s1, 33
	s_cselect_b64 s[0:1], -1, 0
	v_writelane_b32 v252, s0, 34
	s_cmp_eq_u32 s94, 7
	s_nop 0
	v_writelane_b32 v252, s1, 35
	s_cselect_b64 s[0:1], -1, 0
	v_writelane_b32 v252, s0, 36
	s_cmp_eq_u32 s94, 6
	s_nop 0
	v_writelane_b32 v252, s1, 37
	s_cselect_b64 s[0:1], -1, 0
	v_writelane_b32 v252, s0, 38
	s_cmp_eq_u32 s94, 5
	s_nop 0
	v_writelane_b32 v252, s1, 39
	s_cselect_b64 s[0:1], -1, 0
	v_writelane_b32 v252, s0, 40
	s_cmp_eq_u32 s94, 4
	s_nop 0
	v_writelane_b32 v252, s1, 41
	s_cselect_b64 s[0:1], -1, 0
	v_writelane_b32 v252, s0, 42
	s_cmp_eq_u32 s94, 3
	s_nop 0
	v_writelane_b32 v252, s1, 43
	s_cselect_b64 s[0:1], -1, 0
	v_writelane_b32 v252, s0, 44
	s_cmp_eq_u32 s94, 2
	s_nop 0
	v_writelane_b32 v252, s1, 45
	s_cselect_b64 s[0:1], -1, 0
	v_writelane_b32 v252, s0, 46
	s_cmp_eq_u32 s94, 1
	s_nop 0
	v_writelane_b32 v252, s1, 47
	s_cselect_b64 s[0:1], -1, 0
	v_writelane_b32 v252, s0, 48
	s_cmp_eq_u32 s94, 0
	s_nop 0
	v_writelane_b32 v252, s1, 49
	s_cselect_b64 s[0:1], -1, 0
	v_writelane_b32 v252, s0, 50
	s_nop 1
	v_writelane_b32 v252, s1, 51
	s_lshl_b64 s[0:1], s[6:7], 2
	s_add_u32 s0, s26, s0
	s_addc_u32 s1, s27, s1
	s_add_u32 s6, s0, 0x1400
	s_addc_u32 s7, s1, 0
	v_writelane_b32 v252, s6, 52
	s_add_u32 s0, s0, 0x2400
	s_addc_u32 s1, s1, 0
	v_writelane_b32 v252, s7, 53
	v_writelane_b32 v252, s0, 54
	s_nop 1
	v_writelane_b32 v252, s1, 55
	s_add_u32 s0, s26, 0x3400
	s_addc_u32 s1, s27, 0
	v_writelane_b32 v252, s0, 56
	s_nop 1
	v_writelane_b32 v252, s1, 57
	s_add_u32 s0, s26, 0x3500
	s_addc_u32 s1, s27, 0
	v_writelane_b32 v252, s0, 58
	s_cmpk_lt_u32 s19, 0x100
	s_nop 0
	v_writelane_b32 v252, s1, 59
	s_cselect_b64 s[0:1], -1, 0
	v_writelane_b32 v252, s0, 60
	s_cmpk_lt_i32 s20, 0x100
	s_nop 0
	v_writelane_b32 v252, s1, 61
	s_cselect_b64 s[0:1], -1, 0
	v_writelane_b32 v252, s0, 62
	s_add_u32 s5, s26, 0x14000000
	s_nop 0
	v_writelane_b32 v252, s1, 63
	s_addc_u32 s0, s27, 0
	v_writelane_b32 v253, s0, 0
	s_lshr_b32 s0, s20, 1
	s_and_b32 s0, s0, 12
	s_bfe_u32 s1, s95, 0x20004
	s_or_b32 s6, s1, s0
	s_and_b32 s0, s95, 8
	v_writelane_b32 v253, s0, 1
	s_ashr_i32 s0, s20, 5
	s_ashr_i32 s1, s0, 31
	s_lshl_b32 s11, s6, 7
	s_lshl_b32 s6, s4, 4
	s_lshr_b32 s19, s19, 7
	v_writelane_b32 v253, s6, 2
	s_lshl_b64 s[6:7], s[0:1], 12
	s_lshl_b32 s30, s19, 6
	v_writelane_b32 v253, s6, 3
	s_add_u32 s1, s90, s11
	s_nop 0
	v_writelane_b32 v253, s7, 4
	v_writelane_b32 v253, s1, 5
	s_addc_u32 s1, s91, 0
	v_writelane_b32 v253, s1, 6
	s_lshl_b32 s0, s0, 2
	s_bfe_u32 s1, s20, 0x20003
	s_or_b32 s0, s1, s0
	s_ashr_i32 s1, s0, 31
	s_lshl_b64 s[6:7], s[0:1], 19
	s_add_u32 s0, s92, s6
	v_writelane_b32 v253, s0, 7
	s_addc_u32 s0, s93, s7
	v_writelane_b32 v253, s0, 8
	s_add_u32 s0, s22, s6
	v_writelane_b32 v253, s0, 9
	s_addc_u32 s0, s23, s7
	v_writelane_b32 v253, s0, 10
	s_add_u32 s0, s26, s11
	s_addc_u32 s1, s27, 0
	s_add_u32 s0, s0, 0x10000c00
	v_writelane_b32 v253, s0, 11
	s_addc_u32 s0, s1, 0
	v_writelane_b32 v253, s0, 12
	s_add_u32 s0, s24, s11
	v_writelane_b32 v253, s0, 13
	s_addc_u32 s0, s25, 0
	s_cmp_lt_i32 s9, 0
	s_movk_i32 s1, 0xa1
	v_writelane_b32 v253, s0, 14
	s_mul_i32 s0, s9, 0x41
	s_cselect_b32 s1, s1, 0xa0
	s_cselect_b32 s0, s0, s10
	s_mul_i32 s1, s9, s1
	s_movk_i32 s10, 0xc1
	s_cselect_b32 s10, s10, 0xc0
	s_add_i32 s1, s1, s8
	s_mul_hi_i32 s11, s1, 0x66666667
	s_lshr_b32 s12, s11, 31
	s_ashr_i32 s11, s11, 5
	s_add_i32 s11, s11, s12
	s_mul_i32 s12, s11, 0x50
	s_sub_i32 s1, s1, s12
	s_bfe_i32 s12, s1, 0x80000
	s_bfe_u32 s12, s12, 0x3000c
	s_mul_i32 s9, s9, s10
	s_add_i32 s12, s1, s12
	s_add_i32 s9, s9, s8
	s_and_b32 s13, s12, 0xf8
	s_mul_hi_i32 s10, s9, 0x2aaaaaab
	s_sub_i32 s1, s1, s13
	s_lshr_b32 s13, s10, 31
	s_ashr_i32 s10, s10, 4
	s_add_i32 s10, s10, s13
	s_mul_i32 s13, s10, 0x60
	s_sub_i32 s9, s9, s13
	s_bfe_i32 s13, s9, 0x80000
	s_bfe_u32 s13, s13, 0x3000c
	s_add_i32 s13, s9, s13
	s_add_i32 s0, s0, s8
	s_and_b32 s14, s13, 0xf8
	s_ashr_i32 s8, s0, 31
	s_sub_i32 s9, s9, s14
	s_lshr_b32 s14, s8, 22
	s_lshr_b32 s8, s8, 27
	s_add_i32 s14, s0, s14
	s_add_i32 s8, s0, s8
	s_and_b32 s15, s14, 0xfffffc00
	s_and_b32 s16, s8, 0xffe0
	s_sub_i32 s15, s0, s15
	s_sub_i32 s0, s0, s16
	s_bfe_i32 s16, s0, 0x80000
	s_bfe_u32 s16, s16, 0x3000c
	s_add_i32 s16, s0, s16
	s_and_b32 s17, s16, 0xf8
	s_sub_i32 s17, s0, s17
	s_lshl_b32 s0, s11, 3
	s_sext_i32_i8 s1, s1
	s_add_i32 s34, s0, s1
	s_bfe_i32 s1, s13, 0x80000
	s_lshl_b32 s0, s10, 3
	s_sext_i32_i16 s1, s1
	s_sext_i32_i8 s9, s9
	s_add_i32 s36, s0, s9
	s_ashr_i32 s0, s1, 3
	v_writelane_b32 v253, s0, 15
	s_lshr_b32 s0, s1, 3
	s_bfe_i64 s[0:1], s[0:1], 0x100000
	s_lshl_b64 s[0:1], s[0:1], 19
	v_writelane_b32 v253, s0, 16
	s_bfe_i32 s11, s12, 0x80000
	s_sext_i32_i16 s11, s11
	v_writelane_b32 v253, s1, 17
	s_ashr_i32 s0, s14, 10
	s_lshl_b32 s10, s0, 3
	s_sub_i32 s0, 4, s10
	s_min_u32 s12, s0, 8
	s_ashr_i32 s0, s8, 5
	s_bfe_i32 s1, s16, 0x80000
	s_lshl_b32 s0, s0, 3
	s_sext_i32_i16 s1, s1
	s_sext_i32_i8 s8, s17
	s_add_i32 s16, s0, s8
	s_ashr_i32 s0, s1, 3
	v_writelane_b32 v253, s0, 18
	s_ashr_i32 s8, s11, 3
	v_writelane_b32 v253, s8, 19
	s_lshr_b32 s8, s11, 3
	s_bfe_i64 s[8:9], s[8:9], 0x100000
	s_lshr_b32 s0, s1, 3
	s_lshl_b64 s[8:9], s[8:9], 19
	s_bfe_i64 s[0:1], s[0:1], 0x100000
	v_writelane_b32 v253, s8, 20
	s_ashr_i32 s37, s36, 31
	s_ashr_i32 s17, s16, 31
	v_writelane_b32 v253, s9, 21
	s_lshl_b64 s[8:9], s[0:1], 17
	v_writelane_b32 v253, s8, 22
	s_lshl_b64 s[0:1], s[0:1], 19
	s_ashr_i32 s35, s34, 31
	v_writelane_b32 v253, s9, 23
	v_writelane_b32 v253, s0, 24
	v_cvt_f32_ubyte0_e32 v1, s12
	v_cvt_f32_i32_e32 v0, s15
	v_writelane_b32 v253, s1, 25
	s_mov_b32 s0, s36
	v_writelane_b32 v253, s0, 26
	v_rcp_iflag_f32_e32 v2, v1
	s_nop 0
	v_writelane_b32 v253, s1, 27
	s_lshl_b64 s[0:1], s[36:37], 19
	v_writelane_b32 v253, s0, 28
	v_mul_f32_e32 v2, v0, v2
	v_trunc_f32_e32 v2, v2
	v_writelane_b32 v253, s1, 29
	s_lshl_b64 s[0:1], s[16:17], 17
	v_writelane_b32 v253, s0, 30
	v_fma_f32 v0, -v2, v1, v0
	s_nop 0
	v_writelane_b32 v253, s1, 31
	s_mov_b32 s0, s34
	v_writelane_b32 v253, s0, 32
	s_nop 1
	v_writelane_b32 v253, s1, 33
	s_lshl_b64 s[0:1], s[34:35], 19
	v_writelane_b32 v253, s0, 34
	s_nop 1
	v_writelane_b32 v253, s1, 35
	s_mov_b32 s0, s16
	v_writelane_b32 v253, s0, 36
	s_nop 1
	v_writelane_b32 v253, s1, 37
	s_lshl_b64 s[0:1], s[16:17], 19
	s_add_u32 s8, s24, s0
	v_writelane_b32 v253, s0, 38
	s_addc_u32 s9, s25, s1
	s_mov_b32 s24, 0x3f803f80
	v_writelane_b32 v253, s1, 39
	s_add_u32 s0, s8, 0x40000
	v_writelane_b32 v253, s8, 40
	s_addc_u32 s1, s9, 0
	s_nop 0
	v_writelane_b32 v253, s9, 41
	v_writelane_b32 v253, s0, 42
	s_nop 1
	v_writelane_b32 v253, s1, 43
	s_ashr_i32 s0, s15, 30
	s_or_b32 s8, s0, 1
	v_cmp_ge_f32_e64 s[0:1], |v0|, v1
	v_cvt_i32_f32_e32 v0, v2
	s_and_b64 s[0:1], s[0:1], exec
	s_cselect_b32 s0, s8, 0
	v_writelane_b32 v253, s28, 44
	v_readfirstlane_b32 s1, v0
	s_add_i32 s0, s1, s0
	s_mul_i32 s1, s0, s12
	s_sub_i32 s1, s15, s1
	s_sext_i32_i16 s1, s1
	v_writelane_b32 v253, s29, 45
	s_add_i32 s8, s10, s1
	s_sext_i32_i16 s1, s0
	v_writelane_b32 v253, s1, 46
	s_bfe_i64 s[0:1], s[0:1], 0x100000
	s_lshl_b64 s[0:1], s[0:1], 19
	v_writelane_b32 v253, s0, 47
	s_ashr_i32 s9, s8, 31
	v_cndmask_b32_e64 v208, 0, 1, s[28:29]
	v_writelane_b32 v253, s1, 48
	s_mov_b32 s0, s8
	v_writelane_b32 v253, s0, 49
	s_mov_b32 s29, 0
	s_mov_b32 s31, s29
	v_writelane_b32 v253, s1, 50
	s_lshl_b64 s[0:1], s[8:9], 19
	v_writelane_b32 v253, s0, 51
	s_mov_b64 s[14:15], s[22:23]
	s_movk_i32 s9, 0x60
	v_writelane_b32 v253, s1, 52
	s_add_u32 s0, s26, s6
	s_addc_u32 s1, s27, s7
	s_add_u32 s6, s0, 0x1c002000
	v_writelane_b32 v253, s6, 53
	s_addc_u32 s6, s1, 0
	s_add_u32 s0, s0, 0x1d002000
	v_writelane_b32 v253, s6, 54
	s_addc_u32 s1, s1, 0
	v_writelane_b32 v253, s0, 55
	s_bitcmp1_b32 s20, 0
	s_nop 0
	v_writelane_b32 v253, s1, 56
	v_writelane_b32 v253, s30, 57
	s_cselect_b64 s[0:1], -1, 0
	s_bitcmp1_b32 s3, 0
	v_writelane_b32 v253, s31, 58
	v_writelane_b32 v253, s0, 59
	s_nop 1
	v_writelane_b32 v253, s1, 60
	s_cselect_b64 s[0:1], -1, 0
	v_writelane_b32 v253, s0, 61
	s_nop 1
	v_writelane_b32 v253, s1, 62
	s_add_u32 s0, s26, 0x18000040
	s_addc_u32 s1, s27, 0
	v_writelane_b32 v253, s0, 63
	s_add_i32 s6, 0, 0x21400
	s_nop 0
	v_writelane_b32 v254, s1, 0
	s_sub_i32 s0, 0, s19
	v_writelane_b32 v254, s0, 1
	s_add_i32 s1, 0, 0x23fc0
	v_writelane_b32 v254, s1, 2
	s_add_i32 s1, 0, 0x23fc4
	v_writelane_b32 v254, s1, 3
	v_writelane_b32 v254, s6, 4
	s_mov_b32 s0, 0x800000
	s_mov_b32 s1, 0x41000000
	s_mov_b32 s6, s29
	v_writelane_b32 v254, s5, 5
	s_branch .LBB0_207

.LBB0_357:
	s_andn2_saveexec_b64 s[20:21], s[20:21]
	s_cbranch_execz .LBB0_377
	s_mov_b64 s[20:21], exec
	v_readlane_b32 s98, v255, 8
	s_nop 3
	s_cmp_eq_u32 s98, 0
	s_cbranch_scc1 .Lxwb_do_0
	s_branch .Lxwb_skip_0
.Lxwb_do_0:
	buffer_wbl2 sc1
.Lxwb_skip_0:
	s_waitcnt lgkmcnt(0)
	s_waitcnt vmcnt(0)
	v_mbcnt_lo_u32_b32 v1, s20, 0
	v_mbcnt_hi_u32_b32 v1, s21, v1
	v_cmp_eq_u32_e32 vcc, 0, v1
	s_and_saveexec_b64 s[30:31], vcc
	s_cbranch_execz .LBB0_360
	s_bcnt1_i32_b64 s20, s[20:21]
	v_readlane_b32 s6, v252, 56
	v_mov_b32_e32 v2, s20
	v_readlane_b32 s7, v252, 57
	s_nop 4
	global_atomic_add v2, v189, v2, s[6:7] sc0

.LBB0_542:
	s_andn2_saveexec_b64 s[12:13], s[12:13]
	s_cbranch_execz .LBB0_562
	s_mov_b64 s[12:13], exec
	v_readlane_b32 s98, v255, 8
	s_nop 3
	s_cmp_eq_u32 s98, 0
	s_cbranch_scc1 .Lxwb_do_1
	s_branch .Lxwb_skip_1

.Lxwb_skip_1:
	s_waitcnt lgkmcnt(0)
	s_waitcnt vmcnt(0)
	v_mbcnt_lo_u32_b32 v1, s12, 0
	v_mbcnt_hi_u32_b32 v1, s13, v1
	v_cmp_eq_u32_e32 vcc, 0, v1
	s_and_saveexec_b64 s[20:21], vcc
	s_cbranch_execz .LBB0_545
	s_bcnt1_i32_b64 s12, s[12:13]
	v_readlane_b32 s6, v252, 56
	v_mov_b32_e32 v2, s12
	v_readlane_b32 s7, v252, 57
	s_nop 4
	global_atomic_add v2, v189, v2, s[6:7] sc0

.LBB0_698:
	s_andn2_saveexec_b64 s[30:31], s[30:31]
	s_cbranch_execz .LBB0_718
	s_mov_b64 s[30:31], exec
	v_readlane_b32 s98, v255, 8
	s_nop 3
	s_cmp_eq_u32 s98, 0
	s_cbranch_scc1 .Lxwb_do_2
	s_branch .Lxwb_skip_2

.Lxwb_skip_2:
	s_waitcnt lgkmcnt(0)
	s_waitcnt vmcnt(0)
	v_mbcnt_lo_u32_b32 v1, s30, 0
	v_mbcnt_hi_u32_b32 v1, s31, v1
	v_cmp_eq_u32_e32 vcc, 0, v1
	s_and_saveexec_b64 s[34:35], vcc
	s_cbranch_execz .LBB0_701
	s_bcnt1_i32_b64 s30, s[30:31]
	v_readlane_b32 s6, v252, 56
	v_mov_b32_e32 v2, s30
	v_readlane_b32 s7, v252, 57
	s_nop 4
	global_atomic_add v2, v189, v2, s[6:7] sc0

.LBB0_791:
	s_andn2_saveexec_b64 s[12:13], s[12:13]
	s_cbranch_execz .LBB0_205
	s_mov_b64 s[12:13], exec
	v_readlane_b32 s98, v255, 8
	v_readlane_b32 s99, v254, 13
	s_nop 3
	s_cmp_eq_u32 s98, 0
	s_cbranch_scc1 .Lxwb_do_3
	s_cmp_ge_u32 s99, 3
	s_cbranch_scc1 .Lxwb_do_3
	s_branch .Lxwb_skip_3

.Lxwb_skip_3:
	s_waitcnt lgkmcnt(0)
	s_waitcnt vmcnt(0)
	v_mbcnt_lo_u32_b32 v1, s12, 0
	v_mbcnt_hi_u32_b32 v1, s13, v1
	v_cmp_eq_u32_e32 vcc, 0, v1
	s_and_saveexec_b64 s[16:17], vcc
	s_cbranch_execz .LBB0_794
	s_bcnt1_i32_b64 s12, s[12:13]
	v_readlane_b32 s6, v252, 56
	v_mov_b32_e32 v2, s12
	v_readlane_b32 s7, v252, 57
	s_nop 4
	global_atomic_add v2, v189, v2, s[6:7] sc0
